# norm_mod(0) modulation prologue: per-load 64-bit VALU address stepping replaced by SALU stepping of an SGPR base + constant lane offset (saddr loads), on top of the pipelined rounds
# baseline (speedup 1.0000x reference)
.LBB0_101:
	s_waitcnt vmcnt(4)
	v_min_i32_e32 v24, v144, v177
	v_add_u32_e32 v26, 0xffffe000, v24
	v_ashrrev_i32_e32 v25, 31, v24
	v_cmp_gt_i32_e32 vcc, s12, v24
	v_mov_b32_e32 v28, s39
	v_mov_b32_e32 v29, s37
	v_cndmask_b32_e32 v25, 0, v25, vcc
	v_cndmask_b32_e32 v24, v26, v24, vcc
	v_mov_b32_e32 v30, s38
	v_mov_b32_e32 v31, s36
	v_cndmask_b32_e32 v27, v28, v29, vcc
	v_cndmask_b32_e32 v26, v30, v31, vcc
	v_lshlrev_b64 v[24:25], 12, v[24:25]
	v_lshl_add_u64 v[24:25], v[26:27], 0, v[24:25]
	v_lshl_add_u64 v[24:25], v[24:25], 0, v[146:147]
	v_add_u32_e32 v170, 1, v144
	global_load_dwordx4 v[140:143], v[24:25], off nt
	global_load_dwordx4 v[136:139], v[24:25], off offset:1024 nt
	global_load_dwordx4 v[132:135], v[24:25], off offset:2048 nt
	global_load_dwordx4 v[128:131], v[24:25], off offset:3072 nt
	v_min_i32_e32 v24, v170, v177
	v_ashrrev_i32_e32 v25, 31, v24
	v_add_u32_e32 v26, 0xffffe000, v24
	v_cmp_gt_i32_e32 vcc, s12, v24
	v_add_u32_e32 v168, 2, v144
	v_add_u32_e32 v166, 3, v144
	v_cndmask_b32_e32 v25, 0, v25, vcc
	v_cndmask_b32_e32 v24, v26, v24, vcc
	v_cndmask_b32_e32 v27, v28, v29, vcc
	v_cndmask_b32_e32 v26, v30, v31, vcc
	v_lshlrev_b64 v[24:25], 12, v[24:25]
	v_lshl_add_u64 v[24:25], v[26:27], 0, v[24:25]
	v_lshl_add_u64 v[24:25], v[24:25], 0, v[146:147]
	global_load_dwordx4 v[124:127], v[24:25], off nt
	global_load_dwordx4 v[120:123], v[24:25], off offset:1024 nt
	global_load_dwordx4 v[116:119], v[24:25], off offset:2048 nt
	global_load_dwordx4 v[112:115], v[24:25], off offset:3072 nt
	v_min_i32_e32 v24, v168, v177
	v_ashrrev_i32_e32 v25, 31, v24
	v_add_u32_e32 v26, 0xffffe000, v24
	v_cmp_gt_i32_e32 vcc, s12, v24
	v_add_u32_e32 v164, 4, v144
	v_add_u32_e32 v162, 5, v144
	v_cndmask_b32_e32 v25, 0, v25, vcc
	v_cndmask_b32_e32 v24, v26, v24, vcc
	v_cndmask_b32_e32 v27, v28, v29, vcc
	v_cndmask_b32_e32 v26, v30, v31, vcc
	v_lshlrev_b64 v[24:25], 12, v[24:25]
	v_lshl_add_u64 v[24:25], v[26:27], 0, v[24:25]
	v_lshl_add_u64 v[24:25], v[24:25], 0, v[146:147]
	global_load_dwordx4 v[108:111], v[24:25], off nt
	global_load_dwordx4 v[104:107], v[24:25], off offset:1024 nt
	global_load_dwordx4 v[100:103], v[24:25], off offset:2048 nt
	global_load_dwordx4 v[96:99], v[24:25], off offset:3072 nt
	v_min_i32_e32 v24, v166, v177
	v_ashrrev_i32_e32 v25, 31, v24
	v_add_u32_e32 v26, 0xffffe000, v24
	v_cmp_gt_i32_e32 vcc, s12, v24
	v_add_u32_e32 v145, 0xffffe000, v144
	v_ashrrev_i32_e32 v145, 10, v145
	v_cndmask_b32_e32 v25, 0, v25, vcc
	v_cndmask_b32_e32 v24, v26, v24, vcc
	v_cndmask_b32_e32 v27, v28, v29, vcc
	v_cndmask_b32_e32 v26, v30, v31, vcc
	v_lshlrev_b64 v[24:25], 12, v[24:25]
	v_lshl_add_u64 v[24:25], v[26:27], 0, v[24:25]
	v_lshl_add_u64 v[24:25], v[24:25], 0, v[146:147]
	global_load_dwordx4 v[84:87], v[24:25], off nt
	global_load_dwordx4 v[80:83], v[24:25], off offset:1024 nt
	global_load_dwordx4 v[76:79], v[24:25], off offset:2048 nt
	global_load_dwordx4 v[72:75], v[24:25], off offset:3072 nt
	v_min_i32_e32 v24, v164, v177
	v_ashrrev_i32_e32 v25, 31, v24
	v_add_u32_e32 v26, 0xffffe000, v24
	v_cmp_gt_i32_e32 vcc, s12, v24
	v_add_u32_e32 v145, 1, v145
	s_nop 0
	v_cndmask_b32_e32 v25, 0, v25, vcc
	v_cndmask_b32_e32 v24, v26, v24, vcc
	v_cndmask_b32_e32 v27, v28, v29, vcc
	v_cndmask_b32_e32 v26, v30, v31, vcc
	v_lshlrev_b64 v[24:25], 12, v[24:25]
	v_lshl_add_u64 v[24:25], v[26:27], 0, v[24:25]
	v_min_i32_e32 v26, v162, v177
	v_ashrrev_i32_e32 v27, 31, v26
	v_add_u32_e32 v32, 0xffffe000, v26
	v_cmp_gt_i32_e32 vcc, s12, v26
	v_lshl_add_u64 v[24:25], v[24:25], 0, v[146:147]
	s_nop 0
	v_cndmask_b32_e32 v27, 0, v27, vcc
	v_cndmask_b32_e32 v26, v32, v26, vcc
	v_cndmask_b32_e32 v29, v28, v29, vcc
	v_cndmask_b32_e32 v28, v30, v31, vcc
	v_lshlrev_b64 v[26:27], 12, v[26:27]
	v_lshl_add_u64 v[26:27], v[28:29], 0, v[26:27]
	v_lshl_add_u64 v[26:27], v[26:27], 0, v[146:147]
	global_load_dwordx4 v[60:63], v[24:25], off nt
	global_load_dwordx4 v[56:59], v[24:25], off offset:1024 nt
	global_load_dwordx4 v[52:55], v[24:25], off offset:2048 nt
	global_load_dwordx4 v[48:51], v[24:25], off offset:3072 nt
	global_load_dwordx4 v[36:39], v[26:27], off nt
	global_load_dwordx4 v[32:35], v[26:27], off offset:1024 nt
	global_load_dwordx4 v[28:31], v[26:27], off offset:2048 nt
	s_nop 0
	global_load_dwordx4 v[24:27], v[26:27], off offset:3072 nt
	v_cmp_lt_i32_e32 vcc, s13, v144
	s_nop 1
	v_cndmask_b32_e32 v145, 0, v145, vcc
	v_cmp_ne_u32_e32 vcc, v145, v185
	s_and_saveexec_b64 s[6:7], vcc
	s_cbranch_execz .LBB0_111
	v_mad_i64_i32 v[172:173], s[8:9], v145, s3, v[160:161]
	v_readfirstlane_b32 s100, v145
	v_subrev_u32_e32 v222, s24, v160
	s_mul_i32 s100, s100, s3
	s_add_u32 s100, s24, s100
	s_addc_u32 s101, s25, 0
	s_add_u32 s100, s100, 0x1410000
	s_addc_u32 s101, s101, 0
	global_load_dwordx4 v[16:19], v[150:151], off
	global_load_dwordx4 v[20:23], v[152:153], off
	s_mov_b64 s[98:99], s[100:101]
	global_load_dwordx4 v[186:189], v222, s[98:99]
	s_add_u32 s98, s98, 0x1000
	s_addc_u32 s99, s99, 0
	global_load_dwordx4 v[190:193], v222, s[98:99]
	s_add_u32 s98, s98, 0x1d000
	s_addc_u32 s99, s99, 0
	global_load_dwordx4 v[194:197], v222, s[98:99]
	s_add_u32 s98, s98, 0x1000
	s_addc_u32 s99, s99, 0
	global_load_dwordx4 v[198:201], v222, s[98:99]
	s_add_u32 s98, s98, 0x1d000
	s_addc_u32 s99, s99, 0
	global_load_dwordx4 v[202:205], v222, s[98:99]
	s_add_u32 s98, s98, 0x1000
	s_addc_u32 s99, s99, 0
	global_load_dwordx4 v[206:209], v222, s[98:99]
	s_add_u32 s98, s98, 0x1d000
	s_addc_u32 s99, s99, 0
	global_load_dwordx4 v[210:213], v222, s[98:99]
	s_add_u32 s98, s98, 0x1000
	s_addc_u32 s99, s99, 0
	global_load_dwordx4 v[214:217], v222, s[98:99]
	s_add_u32 s98, s98, 0x1d000
	s_addc_u32 s99, s99, 0
	global_load_dwordx4 v[218:221], v222, s[98:99]
	s_add_u32 s98, s98, 0x1000
	s_addc_u32 s99, s99, 0
	global_load_dwordx4 v[226:229], v222, s[98:99]
	s_add_u32 s98, s98, 0x1d000
	s_addc_u32 s99, s99, 0
	global_load_dwordx4 v[230:233], v222, s[98:99]
	s_add_u32 s98, s98, 0x1000
	s_addc_u32 s99, s99, 0
	global_load_dwordx4 v[234:237], v222, s[98:99]
	s_add_u32 s98, s98, 0x1d000
	s_addc_u32 s99, s99, 0
	global_load_dwordx4 v[238:241], v222, s[98:99]
	s_add_u32 s98, s98, 0x1000
	s_addc_u32 s99, s99, 0
	global_load_dwordx4 v[242:245], v222, s[98:99]
	s_add_u32 s98, s98, 0x1d000
	s_addc_u32 s99, s99, 0
	global_load_dwordx4 v[246:249], v222, s[98:99]
	s_add_u32 s98, s98, 0x1000
	s_addc_u32 s99, s99, 0
	global_load_dwordx4 v[250:253], v222, s[98:99]
	s_waitcnt vmcnt(15)
	v_pk_add_f32 v[18:19], v[18:19], v[188:189]
	v_pk_add_f32 v[16:17], v[16:17], v[186:187]
	global_load_dwordx4 v[40:43], v[150:151], off offset:1024
	global_load_dwordx4 v[44:47], v[154:155], off
	s_mov_b64 s[98:99], s[100:101]
	global_load_dwordx4 v[186:189], v222, s[98:99] offset:1024
	s_waitcnt vmcnt(17)
	v_pk_add_f32 v[22:23], v[22:23], v[192:193]
	v_pk_add_f32 v[20:21], v[20:21], v[190:191]
	s_add_u32 s98, s98, 0x1000
	s_addc_u32 s99, s99, 0
	global_load_dwordx4 v[190:193], v222, s[98:99] offset:1024
	s_waitcnt vmcnt(17)
	v_pk_add_f32 v[18:19], v[18:19], v[196:197]
	v_pk_add_f32 v[16:17], v[16:17], v[194:195]
	s_add_u32 s98, s98, 0x1d000
	s_addc_u32 s99, s99, 0
	global_load_dwordx4 v[194:197], v222, s[98:99] offset:1024
	s_waitcnt vmcnt(17)
	v_pk_add_f32 v[22:23], v[22:23], v[200:201]
	v_pk_add_f32 v[20:21], v[20:21], v[198:199]
	s_add_u32 s98, s98, 0x1000
	s_addc_u32 s99, s99, 0
	global_load_dwordx4 v[198:201], v222, s[98:99] offset:1024
	s_waitcnt vmcnt(17)
	v_pk_add_f32 v[18:19], v[18:19], v[204:205]
	v_pk_add_f32 v[16:17], v[16:17], v[202:203]
	s_add_u32 s98, s98, 0x1d000
	s_addc_u32 s99, s99, 0
	global_load_dwordx4 v[202:205], v222, s[98:99] offset:1024
	s_waitcnt vmcnt(17)
	v_pk_add_f32 v[22:23], v[22:23], v[208:209]
	v_pk_add_f32 v[20:21], v[20:21], v[206:207]
	s_add_u32 s98, s98, 0x1000
	s_addc_u32 s99, s99, 0
	global_load_dwordx4 v[206:209], v222, s[98:99] offset:1024
	s_waitcnt vmcnt(17)
	v_pk_add_f32 v[18:19], v[18:19], v[212:213]
	v_pk_add_f32 v[16:17], v[16:17], v[210:211]
	s_add_u32 s98, s98, 0x1d000
	s_addc_u32 s99, s99, 0
	global_load_dwordx4 v[210:213], v222, s[98:99] offset:1024
	s_waitcnt vmcnt(17)
	v_pk_add_f32 v[22:23], v[22:23], v[216:217]
	v_pk_add_f32 v[20:21], v[20:21], v[214:215]
	s_add_u32 s98, s98, 0x1000
	s_addc_u32 s99, s99, 0
	global_load_dwordx4 v[214:217], v222, s[98:99] offset:1024
	s_waitcnt vmcnt(17)
	v_pk_add_f32 v[18:19], v[18:19], v[220:221]
	v_pk_add_f32 v[16:17], v[16:17], v[218:219]
	s_add_u32 s98, s98, 0x1d000
	s_addc_u32 s99, s99, 0
	global_load_dwordx4 v[218:221], v222, s[98:99] offset:1024
	s_waitcnt vmcnt(17)
	v_pk_add_f32 v[22:23], v[22:23], v[228:229]
	v_pk_add_f32 v[20:21], v[20:21], v[226:227]
	s_add_u32 s98, s98, 0x1000
	s_addc_u32 s99, s99, 0
	global_load_dwordx4 v[226:229], v222, s[98:99] offset:1024
	s_waitcnt vmcnt(17)
	v_pk_add_f32 v[18:19], v[18:19], v[232:233]
	v_pk_add_f32 v[16:17], v[16:17], v[230:231]
	s_add_u32 s98, s98, 0x1d000
	s_addc_u32 s99, s99, 0
	global_load_dwordx4 v[230:233], v222, s[98:99] offset:1024
	s_waitcnt vmcnt(17)
	v_pk_add_f32 v[22:23], v[22:23], v[236:237]
	v_pk_add_f32 v[20:21], v[20:21], v[234:235]
	s_add_u32 s98, s98, 0x1000
	s_addc_u32 s99, s99, 0
	global_load_dwordx4 v[234:237], v222, s[98:99] offset:1024
	s_waitcnt vmcnt(17)
	v_pk_add_f32 v[18:19], v[18:19], v[240:241]
	v_pk_add_f32 v[16:17], v[16:17], v[238:239]
	s_add_u32 s98, s98, 0x1d000
	s_addc_u32 s99, s99, 0
	global_load_dwordx4 v[238:241], v222, s[98:99] offset:1024
	s_waitcnt vmcnt(17)
	v_pk_add_f32 v[22:23], v[22:23], v[244:245]
	v_pk_add_f32 v[20:21], v[20:21], v[242:243]
	s_add_u32 s98, s98, 0x1000
	s_addc_u32 s99, s99, 0
	global_load_dwordx4 v[242:245], v222, s[98:99] offset:1024
	s_waitcnt vmcnt(17)
	v_pk_add_f32 v[18:19], v[18:19], v[248:249]
	v_pk_add_f32 v[16:17], v[16:17], v[246:247]
	s_add_u32 s98, s98, 0x1d000
	s_addc_u32 s99, s99, 0
	global_load_dwordx4 v[246:249], v222, s[98:99] offset:1024
	s_waitcnt vmcnt(17)
	v_pk_add_f32 v[22:23], v[22:23], v[252:253]
	v_pk_add_f32 v[20:21], v[20:21], v[250:251]
	s_add_u32 s98, s98, 0x1000
	s_addc_u32 s99, s99, 0
	global_load_dwordx4 v[250:253], v222, s[98:99] offset:1024
	s_waitcnt vmcnt(15)
	v_pk_add_f32 v[42:43], v[42:43], v[188:189]
	v_pk_add_f32 v[40:41], v[40:41], v[186:187]
	global_load_dwordx4 v[64:67], v[150:151], off offset:2048
	global_load_dwordx4 v[68:71], v[156:157], off
	s_mov_b64 s[98:99], s[100:101]
	global_load_dwordx4 v[186:189], v222, s[98:99] offset:2048
	s_waitcnt vmcnt(17)
	v_pk_add_f32 v[46:47], v[46:47], v[192:193]
	v_pk_add_f32 v[44:45], v[44:45], v[190:191]
	s_add_u32 s98, s98, 0x1000
	s_addc_u32 s99, s99, 0
	global_load_dwordx4 v[190:193], v222, s[98:99] offset:2048
	s_waitcnt vmcnt(17)
	v_pk_add_f32 v[42:43], v[42:43], v[196:197]
	v_pk_add_f32 v[40:41], v[40:41], v[194:195]
	s_add_u32 s98, s98, 0x1d000
	s_addc_u32 s99, s99, 0
	global_load_dwordx4 v[194:197], v222, s[98:99] offset:2048
	s_waitcnt vmcnt(17)
	v_pk_add_f32 v[46:47], v[46:47], v[200:201]
	v_pk_add_f32 v[44:45], v[44:45], v[198:199]
	s_add_u32 s98, s98, 0x1000
	s_addc_u32 s99, s99, 0
	global_load_dwordx4 v[198:201], v222, s[98:99] offset:2048
	s_waitcnt vmcnt(17)
	v_pk_add_f32 v[42:43], v[42:43], v[204:205]
	v_pk_add_f32 v[40:41], v[40:41], v[202:203]
	s_add_u32 s98, s98, 0x1d000
	s_addc_u32 s99, s99, 0
	global_load_dwordx4 v[202:205], v222, s[98:99] offset:2048
	s_waitcnt vmcnt(17)
	v_pk_add_f32 v[46:47], v[46:47], v[208:209]
	v_pk_add_f32 v[44:45], v[44:45], v[206:207]
	s_add_u32 s98, s98, 0x1000
	s_addc_u32 s99, s99, 0
	global_load_dwordx4 v[206:209], v222, s[98:99] offset:2048
	s_waitcnt vmcnt(17)
	v_pk_add_f32 v[42:43], v[42:43], v[212:213]
	v_pk_add_f32 v[40:41], v[40:41], v[210:211]
	s_add_u32 s98, s98, 0x1d000
	s_addc_u32 s99, s99, 0
	global_load_dwordx4 v[210:213], v222, s[98:99] offset:2048
	s_waitcnt vmcnt(17)
	v_pk_add_f32 v[46:47], v[46:47], v[216:217]
	v_pk_add_f32 v[44:45], v[44:45], v[214:215]
	s_add_u32 s98, s98, 0x1000
	s_addc_u32 s99, s99, 0
	global_load_dwordx4 v[214:217], v222, s[98:99] offset:2048
	s_waitcnt vmcnt(17)
	v_pk_add_f32 v[42:43], v[42:43], v[220:221]
	v_pk_add_f32 v[40:41], v[40:41], v[218:219]
	s_add_u32 s98, s98, 0x1d000
	s_addc_u32 s99, s99, 0
	global_load_dwordx4 v[218:221], v222, s[98:99] offset:2048
	s_waitcnt vmcnt(17)
	v_pk_add_f32 v[46:47], v[46:47], v[228:229]
	v_pk_add_f32 v[44:45], v[44:45], v[226:227]
	s_add_u32 s98, s98, 0x1000
	s_addc_u32 s99, s99, 0
	global_load_dwordx4 v[226:229], v222, s[98:99] offset:2048
	s_waitcnt vmcnt(17)
	v_pk_add_f32 v[42:43], v[42:43], v[232:233]
	v_pk_add_f32 v[40:41], v[40:41], v[230:231]
	s_add_u32 s98, s98, 0x1d000
	s_addc_u32 s99, s99, 0
	global_load_dwordx4 v[230:233], v222, s[98:99] offset:2048
	s_waitcnt vmcnt(17)
	v_pk_add_f32 v[46:47], v[46:47], v[236:237]
	v_pk_add_f32 v[44:45], v[44:45], v[234:235]
	s_add_u32 s98, s98, 0x1000
	s_addc_u32 s99, s99, 0
	global_load_dwordx4 v[234:237], v222, s[98:99] offset:2048
	s_waitcnt vmcnt(17)
	v_pk_add_f32 v[42:43], v[42:43], v[240:241]
	v_pk_add_f32 v[40:41], v[40:41], v[238:239]
	s_add_u32 s98, s98, 0x1d000
	s_addc_u32 s99, s99, 0
	global_load_dwordx4 v[238:241], v222, s[98:99] offset:2048
	s_waitcnt vmcnt(17)
	v_pk_add_f32 v[46:47], v[46:47], v[244:245]
	v_pk_add_f32 v[44:45], v[44:45], v[242:243]
	s_add_u32 s98, s98, 0x1000
	s_addc_u32 s99, s99, 0
	global_load_dwordx4 v[242:245], v222, s[98:99] offset:2048
	s_waitcnt vmcnt(17)
	v_pk_add_f32 v[42:43], v[42:43], v[248:249]
	v_pk_add_f32 v[40:41], v[40:41], v[246:247]
	s_add_u32 s98, s98, 0x1d000
	s_addc_u32 s99, s99, 0
	global_load_dwordx4 v[246:249], v222, s[98:99] offset:2048
	s_waitcnt vmcnt(17)
	v_pk_add_f32 v[46:47], v[46:47], v[252:253]
	v_pk_add_f32 v[44:45], v[44:45], v[250:251]
	s_add_u32 s98, s98, 0x1000
	s_addc_u32 s99, s99, 0
	global_load_dwordx4 v[250:253], v222, s[98:99] offset:2048
	s_waitcnt vmcnt(15)
	v_pk_add_f32 v[66:67], v[66:67], v[188:189]
	v_pk_add_f32 v[64:65], v[64:65], v[186:187]
	global_load_dwordx4 v[88:91], v[150:151], off offset:3072
	global_load_dwordx4 v[92:95], v[158:159], off
	s_mov_b64 s[98:99], s[100:101]
	global_load_dwordx4 v[186:189], v222, s[98:99] offset:3072
	s_waitcnt vmcnt(17)
	v_pk_add_f32 v[70:71], v[70:71], v[192:193]
	v_pk_add_f32 v[68:69], v[68:69], v[190:191]
	s_add_u32 s98, s98, 0x1000
	s_addc_u32 s99, s99, 0
	global_load_dwordx4 v[190:193], v222, s[98:99] offset:3072
	s_waitcnt vmcnt(17)
	v_pk_add_f32 v[66:67], v[66:67], v[196:197]
	v_pk_add_f32 v[64:65], v[64:65], v[194:195]
	s_add_u32 s98, s98, 0x1d000
	s_addc_u32 s99, s99, 0
	global_load_dwordx4 v[194:197], v222, s[98:99] offset:3072
	s_waitcnt vmcnt(17)
	v_pk_add_f32 v[70:71], v[70:71], v[200:201]
	v_pk_add_f32 v[68:69], v[68:69], v[198:199]
	s_add_u32 s98, s98, 0x1000
	s_addc_u32 s99, s99, 0
	global_load_dwordx4 v[198:201], v222, s[98:99] offset:3072
	s_waitcnt vmcnt(17)
	v_pk_add_f32 v[66:67], v[66:67], v[204:205]
	v_pk_add_f32 v[64:65], v[64:65], v[202:203]
	s_add_u32 s98, s98, 0x1d000
	s_addc_u32 s99, s99, 0
	global_load_dwordx4 v[202:205], v222, s[98:99] offset:3072
	s_waitcnt vmcnt(17)
	v_pk_add_f32 v[70:71], v[70:71], v[208:209]
	v_pk_add_f32 v[68:69], v[68:69], v[206:207]
	s_add_u32 s98, s98, 0x1000
	s_addc_u32 s99, s99, 0
	global_load_dwordx4 v[206:209], v222, s[98:99] offset:3072
	s_waitcnt vmcnt(17)
	v_pk_add_f32 v[66:67], v[66:67], v[212:213]
	v_pk_add_f32 v[64:65], v[64:65], v[210:211]
	s_add_u32 s98, s98, 0x1d000
	s_addc_u32 s99, s99, 0
	global_load_dwordx4 v[210:213], v222, s[98:99] offset:3072
	s_waitcnt vmcnt(17)
	v_pk_add_f32 v[70:71], v[70:71], v[216:217]
	v_pk_add_f32 v[68:69], v[68:69], v[214:215]
	s_add_u32 s98, s98, 0x1000
	s_addc_u32 s99, s99, 0
	global_load_dwordx4 v[214:217], v222, s[98:99] offset:3072
	s_waitcnt vmcnt(17)
	v_pk_add_f32 v[66:67], v[66:67], v[220:221]
	v_pk_add_f32 v[64:65], v[64:65], v[218:219]
	s_add_u32 s98, s98, 0x1d000
	s_addc_u32 s99, s99, 0
	global_load_dwordx4 v[218:221], v222, s[98:99] offset:3072
	s_waitcnt vmcnt(17)
	v_pk_add_f32 v[70:71], v[70:71], v[228:229]
	v_pk_add_f32 v[68:69], v[68:69], v[226:227]
	s_add_u32 s98, s98, 0x1000
	s_addc_u32 s99, s99, 0
	global_load_dwordx4 v[226:229], v222, s[98:99] offset:3072
	s_waitcnt vmcnt(17)
	v_pk_add_f32 v[66:67], v[66:67], v[232:233]
	v_pk_add_f32 v[64:65], v[64:65], v[230:231]
	s_add_u32 s98, s98, 0x1d000
	s_addc_u32 s99, s99, 0
	global_load_dwordx4 v[230:233], v222, s[98:99] offset:3072
	s_waitcnt vmcnt(17)
	v_pk_add_f32 v[70:71], v[70:71], v[236:237]
	v_pk_add_f32 v[68:69], v[68:69], v[234:235]
	s_add_u32 s98, s98, 0x1000
	s_addc_u32 s99, s99, 0
	global_load_dwordx4 v[234:237], v222, s[98:99] offset:3072
	s_waitcnt vmcnt(17)
	v_pk_add_f32 v[66:67], v[66:67], v[240:241]
	v_pk_add_f32 v[64:65], v[64:65], v[238:239]
	s_add_u32 s98, s98, 0x1d000
	s_addc_u32 s99, s99, 0
	global_load_dwordx4 v[238:241], v222, s[98:99] offset:3072
	s_waitcnt vmcnt(17)
	v_pk_add_f32 v[70:71], v[70:71], v[244:245]
	v_pk_add_f32 v[68:69], v[68:69], v[242:243]
	s_add_u32 s98, s98, 0x1000
	s_addc_u32 s99, s99, 0
	global_load_dwordx4 v[242:245], v222, s[98:99] offset:3072
	s_waitcnt vmcnt(17)
	v_pk_add_f32 v[66:67], v[66:67], v[248:249]
	v_pk_add_f32 v[64:65], v[64:65], v[246:247]
	s_add_u32 s98, s98, 0x1d000
	s_addc_u32 s99, s99, 0
	global_load_dwordx4 v[246:249], v222, s[98:99] offset:3072
	s_waitcnt vmcnt(17)
	v_pk_add_f32 v[70:71], v[70:71], v[252:253]
	v_pk_add_f32 v[68:69], v[68:69], v[250:251]
	s_add_u32 s98, s98, 0x1000
	s_addc_u32 s99, s99, 0
	global_load_dwordx4 v[250:253], v222, s[98:99] offset:3072
	s_waitcnt vmcnt(15)
	v_pk_add_f32 v[90:91], v[90:91], v[188:189]
	v_pk_add_f32 v[88:89], v[88:89], v[186:187]
	s_waitcnt vmcnt(14)
	v_pk_add_f32 v[94:95], v[94:95], v[192:193]
	v_pk_add_f32 v[92:93], v[92:93], v[190:191]
	s_waitcnt vmcnt(13)
	v_pk_add_f32 v[90:91], v[90:91], v[196:197]
	v_pk_add_f32 v[88:89], v[88:89], v[194:195]
	s_waitcnt vmcnt(12)
	v_pk_add_f32 v[94:95], v[94:95], v[200:201]
	v_pk_add_f32 v[92:93], v[92:93], v[198:199]
	s_waitcnt vmcnt(11)
	v_pk_add_f32 v[90:91], v[90:91], v[204:205]
	v_pk_add_f32 v[88:89], v[88:89], v[202:203]
	s_waitcnt vmcnt(10)
	v_pk_add_f32 v[94:95], v[94:95], v[208:209]
	v_pk_add_f32 v[92:93], v[92:93], v[206:207]
	s_waitcnt vmcnt(9)
	v_pk_add_f32 v[90:91], v[90:91], v[212:213]
	v_pk_add_f32 v[88:89], v[88:89], v[210:211]
	s_waitcnt vmcnt(8)
	v_pk_add_f32 v[94:95], v[94:95], v[216:217]
	v_pk_add_f32 v[92:93], v[92:93], v[214:215]
	s_waitcnt vmcnt(7)
	v_pk_add_f32 v[90:91], v[90:91], v[220:221]
	v_pk_add_f32 v[88:89], v[88:89], v[218:219]
	s_waitcnt vmcnt(6)
	v_pk_add_f32 v[94:95], v[94:95], v[228:229]
	v_pk_add_f32 v[92:93], v[92:93], v[226:227]
	s_waitcnt vmcnt(5)
	v_pk_add_f32 v[90:91], v[90:91], v[232:233]
	v_pk_add_f32 v[88:89], v[88:89], v[230:231]
	s_waitcnt vmcnt(4)
	v_pk_add_f32 v[94:95], v[94:95], v[236:237]
	v_pk_add_f32 v[92:93], v[92:93], v[234:235]
	s_waitcnt vmcnt(3)
	v_pk_add_f32 v[90:91], v[90:91], v[240:241]
	v_pk_add_f32 v[88:89], v[88:89], v[238:239]
	s_waitcnt vmcnt(2)
	v_pk_add_f32 v[94:95], v[94:95], v[244:245]
	v_pk_add_f32 v[92:93], v[92:93], v[242:243]
	s_waitcnt vmcnt(1)
	v_pk_add_f32 v[90:91], v[90:91], v[248:249]
	v_pk_add_f32 v[88:89], v[88:89], v[246:247]
	s_waitcnt vmcnt(0)
	v_pk_add_f32 v[94:95], v[94:95], v[252:253]
	v_pk_add_f32 v[92:93], v[92:93], v[250:251]
	v_mov_b32_e32 v185, v145
